# same as previous (invalidate issued by wave 1 during the barrier); the wave id is read from lane 0 explicitly
# speedup vs baseline: 1.0159x; 1.0010x over previous
.LBB0_664:
	v_readlane_b32 s0, v254, 24
	v_readlane_b32 s1, v254, 25
	s_andn2_b64 vcc, exec, s[0:1]
	v_readlane_b32 s19, v254, 20
	s_cbranch_vccnz .LBB0_22
	s_waitcnt vmcnt(0)
	s_waitcnt vmcnt(0)
	s_barrier
	v_readlane_b32 s0, v224, 0
	s_cmp_eq_u32 s0, 64
	s_cbranch_scc0 .Lbi_skip
	s_mov_b64 s[2:3], exec
	s_mov_b64 exec, 1
	buffer_inv sc1
	s_waitcnt vmcnt(0)
	s_mov_b64 exec, s[2:3]
